# EpiHalo: write-through halo stores now cover whole 64-byte runs per row (upper/lower lane halves exchanged with v_permlane32_swap) instead of 16-byte pieces
# speedup vs baseline: 1.0235x; 1.0110x over previous
;     __device__ __forceinline__ void operator()(const f32x4 (&acc)[2][2][4][2], const Unit& u, int wr, int wc, int fr, int fq) const {
;     ...
;                 const int hr = u.pm * 256 + ai * 128 + wr * 64 + m * 16 + fr;
;                 const int orig = 32 * hr - 31 * (hr & 1) - 2;
;                 const float rs = orig >= 0 ? rsqrtf(SS[orig] * (1.0f / D) + EPS) : 0.f;
; #pragma unroll
;                 for (int bj = 0; bj < 2; ++bj) {
;                     const int col0 = u.pn * 256 + bj * 128 + wc * 32 + fq * 8;
;                     float* p = HALO + (size_t)hr * FF2 + col0;
;                     const f32x4 h0 = acc[ai][bj][m][0] * rs, h1 = acc[ai][bj][m][1] * rs;
;                     asm volatile("global_store_dwordx4 %0, %1, off sc1\n\ts_nop 1" :: "v"(p), "v"(h0) : "memory");
;                     asm volatile("global_store_dwordx4 %0, %1, off offset:16 sc1\n\ts_nop 1" :: "v"(p), "v"(h1) : "memory");
.LBB0_669:
	s_lshl_b32 s23, s46, 8
	v_mbcnt_lo_u32_b32 v244, -1, 0
	v_mbcnt_hi_u32_b32 v244, -1, v244
	v_lshlrev_b32_e32 v245, 26, v244
	v_ashrrev_i32_e32 v245, 31, v245
	v_and_b32_e32 v244, 0xffffffd0, v245
	v_mov_b32_e32 v241, 0
	v_add_u32_e32 v240, s23, v147
	v_lshl_add_u32 v240, v240, 5, v149
	v_lshl_add_u64 v[242:243], v[240:241], 2, s[10:11]
	global_load_dword v248, v[242:243], off offset:-8
	v_add_u32_e32 v240, s23, v150
	v_lshl_add_u32 v240, v240, 5, v149
	v_lshl_add_u64 v[242:243], v[240:241], 2, s[10:11]
	global_load_dword v249, v[242:243], off offset:-8
	v_add_u32_e32 v240, s23, v151
	v_lshl_add_u32 v240, v240, 5, v149
	v_lshl_add_u64 v[242:243], v[240:241], 2, s[10:11]
	global_load_dword v250, v[242:243], off offset:-8
	v_add_u32_e32 v240, s23, v153
	v_lshl_add_u32 v240, v240, 5, v149
	v_lshl_add_u64 v[242:243], v[240:241], 2, s[10:11]
	global_load_dword v251, v[242:243], off offset:-8
	v_add_u32_e32 v240, s23, v147
	v_add_u32_e32 v240, 0x80, v240
	v_lshl_add_u32 v240, v240, 5, v149
	v_lshl_add_u64 v[242:243], v[240:241], 2, s[10:11]
	global_load_dword v252, v[242:243], off offset:-8
	v_add_u32_e32 v240, s23, v147
	v_add_u32_e32 v240, 0x90, v240
	v_lshl_add_u32 v240, v240, 5, v149
	v_lshl_add_u64 v[242:243], v[240:241], 2, s[10:11]
	global_load_dword v253, v[242:243], off offset:-8
	v_add_u32_e32 v240, s23, v147
	v_add_u32_e32 v240, 0xa0, v240
	v_lshl_add_u32 v240, v240, 5, v149
	v_lshl_add_u64 v[242:243], v[240:241], 2, s[10:11]
	global_load_dword v254, v[242:243], off offset:-8
	v_add_u32_e32 v240, s23, v147
	v_add_u32_e32 v240, 0xb0, v240
	v_lshl_add_u32 v240, v240, 5, v149
	v_lshl_add_u64 v[242:243], v[240:241], 2, s[10:11]
	global_load_dword v255, v[242:243], off offset:-8
	s_waitcnt vmcnt(0)
	v_add_u32_e32 v164, s23, v147
	v_lshl_add_u32 v136, v164, 5, v149
	v_cmp_lt_i32_e32 vcc, 1, v136
	v_mov_b32_e32 v144, 0
	v_mov_b32_e32 v146, 0
	s_and_saveexec_b64 s[46:47], vcc
	s_cbranch_execz .LBB0_671
	v_lshl_add_u64 v[142:143], v[136:137], 2, s[10:11]
	v_mov_b32_e32 v136, v248
	v_fmamk_f32 v136, v136, 0x3a800000, v163
	v_mul_f32_e32 v142, 0x4b800000, v136
	v_cmp_gt_f32_e32 vcc, s60, v136
	s_nop 1
	v_cndmask_b32_e32 v136, v136, v142, vcc
	v_rsq_f32_e32 v136, v136
	s_nop 0
	v_mul_f32_e32 v142, 0x45800000, v136
	v_cndmask_b32_e32 v146, v136, v142, vcc
.LBB0_671:
	s_or_b64 exec, exec, s[46:47]
	v_lshl_or_b32 v142, s44, 8, v159
	v_mov_b64_e32 v[166:167], s[12:13]
	v_mad_i64_i32 v[166:167], s[44:45], v164, s61, v[166:167]
	v_ashrrev_i32_e32 v143, 31, v142
	v_lshl_add_u64 v[166:167], v[142:143], 2, v[166:167]
	v_pk_mul_f32 v[126:127], v[126:127], v[146:147] op_sel_hi:[1,0]
	v_pk_mul_f32 v[124:125], v[124:125], v[146:147] op_sel_hi:[1,0]
	v_pk_mul_f32 v[122:123], v[122:123], v[146:147] op_sel_hi:[1,0]
	s_nop 1
	v_pk_mul_f32 v[120:121], v[120:121], v[146:147] op_sel_hi:[1,0]
	v_pk_mul_f32 v[118:119], v[118:119], v[146:147] op_sel_hi:[1,0]
	v_lshl_add_u64 v[166:167], v[166:167], 0, v[244:245]
	s_nop 1
	v_permlane32_swap_b32_e32 v124, v120
	v_permlane32_swap_b32_e32 v125, v121
	v_permlane32_swap_b32_e32 v126, v122
	v_permlane32_swap_b32_e32 v127, v123
	global_store_dwordx4 v[166:167], v[124:127], off sc1
	global_store_dwordx4 v[166:167], v[120:123], off offset:64 sc1
	s_nop 1
	v_lshl_add_u64 v[120:121], v[166:167], 0, s[20:21]
	v_pk_mul_f32 v[116:117], v[116:117], v[146:147] op_sel_hi:[1,0]
	v_pk_mul_f32 v[112:113], v[112:113], v[146:147] op_sel_hi:[1,0]
	s_nop 1
	v_pk_mul_f32 v[114:115], v[114:115], v[146:147] op_sel_hi:[1,0]
	s_nop 0
	s_nop 1
	v_permlane32_swap_b32_e32 v116, v112
	v_permlane32_swap_b32_e32 v117, v113
	v_permlane32_swap_b32_e32 v118, v114
	v_permlane32_swap_b32_e32 v119, v115
	global_store_dwordx4 v[120:121], v[116:119], off sc1
	global_store_dwordx4 v[120:121], v[112:115], off offset:64 sc1
	s_nop 1
	v_add_u32_e32 v112, s23, v150
	v_lshl_add_u32 v136, v112, 5, v149
	v_cmp_lt_i32_e32 vcc, 1, v136
	s_and_saveexec_b64 s[44:45], vcc
	s_cbranch_execz .LBB0_673
	v_lshl_add_u64 v[114:115], v[136:137], 2, s[10:11]
	v_mov_b32_e32 v113, v249
	v_fmamk_f32 v113, v113, 0x3a800000, v163
	v_mul_f32_e32 v114, 0x4b800000, v113
	v_cmp_gt_f32_e32 vcc, s60, v113
	s_nop 1
	v_cndmask_b32_e32 v113, v113, v114, vcc
	v_rsq_f32_e32 v113, v113
	s_nop 0
	v_mul_f32_e32 v114, 0x45800000, v113
	v_cndmask_b32_e32 v144, v113, v114, vcc
.LBB0_673:
	s_or_b64 exec, exec, s[44:45]
	v_mov_b64_e32 v[114:115], s[12:13]
	v_mad_i64_i32 v[112:113], s[44:45], v112, s61, v[114:115]
	v_lshl_add_u64 v[112:113], v[142:143], 2, v[112:113]
	v_pk_mul_f32 v[110:111], v[110:111], v[144:145] op_sel_hi:[1,0]
	v_pk_mul_f32 v[108:109], v[108:109], v[144:145] op_sel_hi:[1,0]
	v_pk_mul_f32 v[106:107], v[106:107], v[144:145] op_sel_hi:[1,0]
	s_nop 1
	v_pk_mul_f32 v[104:105], v[104:105], v[144:145] op_sel_hi:[1,0]
	v_pk_mul_f32 v[102:103], v[102:103], v[144:145] op_sel_hi:[1,0]
	v_lshl_add_u64 v[112:113], v[112:113], 0, v[244:245]
	s_nop 1
	v_permlane32_swap_b32_e32 v108, v104
	v_permlane32_swap_b32_e32 v109, v105
	v_permlane32_swap_b32_e32 v110, v106
	v_permlane32_swap_b32_e32 v111, v107
	global_store_dwordx4 v[112:113], v[108:111], off sc1
	global_store_dwordx4 v[112:113], v[104:107], off offset:64 sc1
	s_nop 1
	v_lshl_add_u64 v[104:105], v[112:113], 0, s[20:21]
	v_pk_mul_f32 v[100:101], v[100:101], v[144:145] op_sel_hi:[1,0]
	v_pk_mul_f32 v[96:97], v[96:97], v[144:145] op_sel_hi:[1,0]
	s_nop 1
	v_pk_mul_f32 v[98:99], v[98:99], v[144:145] op_sel_hi:[1,0]
	s_nop 0
	s_nop 1
	v_permlane32_swap_b32_e32 v100, v96
	v_permlane32_swap_b32_e32 v101, v97
	v_permlane32_swap_b32_e32 v102, v98
	v_permlane32_swap_b32_e32 v103, v99
	global_store_dwordx4 v[104:105], v[100:103], off sc1
	global_store_dwordx4 v[104:105], v[96:99], off offset:64 sc1
	s_nop 1
	v_add_u32_e32 v97, s23, v151
	v_lshl_add_u32 v136, v97, 5, v149
	v_cmp_lt_i32_e32 vcc, 1, v136
	v_mov_b32_e32 v96, 0
	v_mov_b32_e32 v98, 0
	s_and_saveexec_b64 s[44:45], vcc
	s_cbranch_execz .LBB0_675
	v_lshl_add_u64 v[98:99], v[136:137], 2, s[10:11]
	v_mov_b32_e32 v98, v250
	v_fmamk_f32 v98, v98, 0x3a800000, v163
	v_mul_f32_e32 v99, 0x4b800000, v98
	v_cmp_gt_f32_e32 vcc, s60, v98
	s_nop 1
	v_cndmask_b32_e32 v98, v98, v99, vcc
	v_rsq_f32_e32 v98, v98
	s_nop 0
	v_mul_f32_e32 v99, 0x45800000, v98
	v_cndmask_b32_e32 v98, v98, v99, vcc
;     __device__ __forceinline__ void operator()(const f32x4 (&acc)[2][2][4][2], const Unit& u, int wr, int wc, int fr, int fq) const {
;     ...
;                 const int hr = u.pm * 256 + ai * 128 + wr * 64 + m * 16 + fr;
;                 const int orig = 32 * hr - 31 * (hr & 1) - 2;
;                 const float rs = orig >= 0 ? rsqrtf(SS[orig] * (1.0f / D) + EPS) : 0.f;
; #pragma unroll
;                 for (int bj = 0; bj < 2; ++bj) {
;                     const int col0 = u.pn * 256 + bj * 128 + wc * 32 + fq * 8;
;                     float* p = HALO + (size_t)hr * FF2 + col0;
;                     const f32x4 h0 = acc[ai][bj][m][0] * rs, h1 = acc[ai][bj][m][1] * rs;
;                     asm volatile("global_store_dwordx4 %0, %1, off sc1\n\ts_nop 1" :: "v"(p), "v"(h0) : "memory");
;                     asm volatile("global_store_dwordx4 %0, %1, off offset:16 sc1\n\ts_nop 1" :: "v"(p), "v"(h1) : "memory");
.LBB0_675:
	s_or_b64 exec, exec, s[44:45]
	v_mov_b64_e32 v[100:101], s[12:13]
	v_mad_i64_i32 v[100:101], s[44:45], v97, s61, v[100:101]
	v_lshl_add_u64 v[100:101], v[142:143], 2, v[100:101]
	v_pk_mul_f32 v[94:95], v[94:95], v[98:99] op_sel_hi:[1,0]
	v_pk_mul_f32 v[92:93], v[92:93], v[98:99] op_sel_hi:[1,0]
	v_pk_mul_f32 v[90:91], v[90:91], v[98:99] op_sel_hi:[1,0]
	s_nop 1
	v_pk_mul_f32 v[88:89], v[88:89], v[98:99] op_sel_hi:[1,0]
	v_pk_mul_f32 v[86:87], v[86:87], v[98:99] op_sel_hi:[1,0]
	v_lshl_add_u64 v[100:101], v[100:101], 0, v[244:245]
	s_nop 1
	v_permlane32_swap_b32_e32 v92, v88
	v_permlane32_swap_b32_e32 v93, v89
	v_permlane32_swap_b32_e32 v94, v90
	v_permlane32_swap_b32_e32 v95, v91
	global_store_dwordx4 v[100:101], v[92:95], off sc1
	global_store_dwordx4 v[100:101], v[88:91], off offset:64 sc1
	s_nop 1
	v_lshl_add_u64 v[88:89], v[100:101], 0, s[20:21]
	v_pk_mul_f32 v[84:85], v[84:85], v[98:99] op_sel_hi:[1,0]
	v_pk_mul_f32 v[80:81], v[80:81], v[98:99] op_sel_hi:[1,0]
	s_nop 1
	v_pk_mul_f32 v[82:83], v[82:83], v[98:99] op_sel_hi:[1,0]
	s_nop 0
	s_nop 1
	v_permlane32_swap_b32_e32 v84, v80
	v_permlane32_swap_b32_e32 v85, v81
	v_permlane32_swap_b32_e32 v86, v82
	v_permlane32_swap_b32_e32 v87, v83
	global_store_dwordx4 v[88:89], v[84:87], off sc1
	global_store_dwordx4 v[88:89], v[80:83], off offset:64 sc1
	s_nop 1
	v_add_u32_e32 v80, s23, v153
	v_lshl_add_u32 v136, v80, 5, v149
	v_cmp_lt_i32_e32 vcc, 1, v136
	s_and_saveexec_b64 s[44:45], vcc
	s_cbranch_execz .LBB0_677
	v_lshl_add_u64 v[82:83], v[136:137], 2, s[10:11]
	v_mov_b32_e32 v81, v251
	v_fmamk_f32 v81, v81, 0x3a800000, v163
	v_mul_f32_e32 v82, 0x4b800000, v81
	v_cmp_gt_f32_e32 vcc, s60, v81
	s_nop 1
	v_cndmask_b32_e32 v81, v81, v82, vcc
	v_rsq_f32_e32 v81, v81
	s_nop 0
	v_mul_f32_e32 v82, 0x45800000, v81
	v_cndmask_b32_e32 v96, v81, v82, vcc
.LBB0_677:
	s_or_b64 exec, exec, s[44:45]
	v_mov_b64_e32 v[82:83], s[12:13]
	v_mad_i64_i32 v[80:81], s[44:45], v80, s61, v[82:83]
	v_lshl_add_u64 v[80:81], v[142:143], 2, v[80:81]
	v_pk_mul_f32 v[78:79], v[78:79], v[96:97] op_sel_hi:[1,0]
	v_pk_mul_f32 v[76:77], v[76:77], v[96:97] op_sel_hi:[1,0]
	v_pk_mul_f32 v[74:75], v[74:75], v[96:97] op_sel_hi:[1,0]
	s_nop 1
	v_pk_mul_f32 v[72:73], v[72:73], v[96:97] op_sel_hi:[1,0]
	v_pk_mul_f32 v[70:71], v[70:71], v[96:97] op_sel_hi:[1,0]
	v_lshl_add_u64 v[80:81], v[80:81], 0, v[244:245]
	s_nop 1
	v_permlane32_swap_b32_e32 v76, v72
	v_permlane32_swap_b32_e32 v77, v73
	v_permlane32_swap_b32_e32 v78, v74
	v_permlane32_swap_b32_e32 v79, v75
	global_store_dwordx4 v[80:81], v[76:79], off sc1
	global_store_dwordx4 v[80:81], v[72:75], off offset:64 sc1
	s_nop 1
	v_lshl_add_u64 v[72:73], v[80:81], 0, s[20:21]
	v_pk_mul_f32 v[68:69], v[68:69], v[96:97] op_sel_hi:[1,0]
	v_pk_mul_f32 v[64:65], v[64:65], v[96:97] op_sel_hi:[1,0]
	s_nop 1
	v_pk_mul_f32 v[66:67], v[66:67], v[96:97] op_sel_hi:[1,0]
	s_nop 0
	s_nop 1
	v_permlane32_swap_b32_e32 v68, v64
	v_permlane32_swap_b32_e32 v69, v65
	v_permlane32_swap_b32_e32 v70, v66
	v_permlane32_swap_b32_e32 v71, v67
	global_store_dwordx4 v[72:73], v[68:71], off sc1
	global_store_dwordx4 v[72:73], v[64:67], off offset:64 sc1
	s_nop 1
	v_add_u32_e32 v65, 0x80, v164
	v_lshl_add_u32 v136, v65, 5, v149
	v_cmp_lt_i32_e32 vcc, 1, v136
	v_mov_b32_e32 v64, 0
	v_mov_b32_e32 v66, 0
	s_and_saveexec_b64 s[44:45], vcc
	s_cbranch_execz .LBB0_679
	v_lshl_add_u64 v[66:67], v[136:137], 2, s[10:11]
	v_mov_b32_e32 v66, v252
	v_fmamk_f32 v66, v66, 0x3a800000, v163
	v_mul_f32_e32 v67, 0x4b800000, v66
	v_cmp_gt_f32_e32 vcc, s60, v66
	s_nop 1
	v_cndmask_b32_e32 v66, v66, v67, vcc
	v_rsq_f32_e32 v66, v66
	s_nop 0
	v_mul_f32_e32 v67, 0x45800000, v66
	v_cndmask_b32_e32 v66, v66, v67, vcc
.LBB0_679:
	s_or_b64 exec, exec, s[44:45]
	v_mov_b64_e32 v[68:69], s[12:13]
	v_mad_i64_i32 v[68:69], s[44:45], v65, s61, v[68:69]
	v_lshl_add_u64 v[68:69], v[142:143], 2, v[68:69]
	v_pk_mul_f32 v[62:63], v[62:63], v[66:67] op_sel_hi:[1,0]
	v_pk_mul_f32 v[60:61], v[60:61], v[66:67] op_sel_hi:[1,0]
	v_pk_mul_f32 v[58:59], v[58:59], v[66:67] op_sel_hi:[1,0]
	s_nop 1
	v_pk_mul_f32 v[56:57], v[56:57], v[66:67] op_sel_hi:[1,0]
	v_pk_mul_f32 v[54:55], v[54:55], v[66:67] op_sel_hi:[1,0]
	v_lshl_add_u64 v[68:69], v[68:69], 0, v[244:245]
	s_nop 1
	v_permlane32_swap_b32_e32 v60, v56
	v_permlane32_swap_b32_e32 v61, v57
	v_permlane32_swap_b32_e32 v62, v58
	v_permlane32_swap_b32_e32 v63, v59
	global_store_dwordx4 v[68:69], v[60:63], off sc1
	global_store_dwordx4 v[68:69], v[56:59], off offset:64 sc1
	s_nop 1
	v_lshl_add_u64 v[56:57], v[68:69], 0, s[20:21]
	v_pk_mul_f32 v[52:53], v[52:53], v[66:67] op_sel_hi:[1,0]
	v_pk_mul_f32 v[48:49], v[48:49], v[66:67] op_sel_hi:[1,0]
	s_nop 1
	v_pk_mul_f32 v[50:51], v[50:51], v[66:67] op_sel_hi:[1,0]
	s_nop 0
	s_nop 1
	v_permlane32_swap_b32_e32 v52, v48
	v_permlane32_swap_b32_e32 v53, v49
	v_permlane32_swap_b32_e32 v54, v50
	v_permlane32_swap_b32_e32 v55, v51
	global_store_dwordx4 v[56:57], v[52:55], off sc1
	global_store_dwordx4 v[56:57], v[48:51], off offset:64 sc1
	s_nop 1
	v_add_u32_e32 v48, 0x90, v164
	v_lshl_add_u32 v136, v48, 5, v149
	v_cmp_lt_i32_e32 vcc, 1, v136
	s_and_saveexec_b64 s[44:45], vcc
	s_cbranch_execz .LBB0_681
	v_lshl_add_u64 v[50:51], v[136:137], 2, s[10:11]
	v_mov_b32_e32 v49, v253
	v_fmamk_f32 v49, v49, 0x3a800000, v163
	v_mul_f32_e32 v50, 0x4b800000, v49
	v_cmp_gt_f32_e32 vcc, s60, v49
	s_nop 1
	v_cndmask_b32_e32 v49, v49, v50, vcc
	v_rsq_f32_e32 v49, v49
	s_nop 0
	v_mul_f32_e32 v50, 0x45800000, v49
	v_cndmask_b32_e32 v64, v49, v50, vcc
;     __device__ __forceinline__ void operator()(const f32x4 (&acc)[2][2][4][2], const Unit& u, int wr, int wc, int fr, int fq) const {
;     ...
;                 const int hr = u.pm * 256 + ai * 128 + wr * 64 + m * 16 + fr;
;                 const int orig = 32 * hr - 31 * (hr & 1) - 2;
;                 const float rs = orig >= 0 ? rsqrtf(SS[orig] * (1.0f / D) + EPS) : 0.f;
; #pragma unroll
;                 for (int bj = 0; bj < 2; ++bj) {
;                     const int col0 = u.pn * 256 + bj * 128 + wc * 32 + fq * 8;
;                     float* p = HALO + (size_t)hr * FF2 + col0;
;                     const f32x4 h0 = acc[ai][bj][m][0] * rs, h1 = acc[ai][bj][m][1] * rs;
;                     asm volatile("global_store_dwordx4 %0, %1, off sc1\n\ts_nop 1" :: "v"(p), "v"(h0) : "memory");
;                     asm volatile("global_store_dwordx4 %0, %1, off offset:16 sc1\n\ts_nop 1" :: "v"(p), "v"(h1) : "memory");
;     __device__ __forceinline__ void done(const Unit& u) const {
;         if (done_pm == -2 || (done_pm >= 0 && u.pm != done_pm)) return;
;         asm volatile("s_waitcnt vmcnt(0)" ::: "memory");
;         asm volatile("" ::: "memory"); __builtin_amdgcn_s_barrier(); asm volatile("" ::: "memory");
;         if (threadIdx.x < 64) {
;             if (done_rel) { __builtin_amdgcn_fence(__ATOMIC_RELEASE, "agent"); asm volatile("s_waitcnt vmcnt(0)" ::: "memory"); }
;             if (threadIdx.x == 0) __hip_atomic_fetch_add(done_ctr, 1u, __ATOMIC_RELAXED, __HIP_MEMORY_SCOPE_AGENT);
;         }
.LBB0_681:
	s_or_b64 exec, exec, s[44:45]
	v_mov_b64_e32 v[50:51], s[12:13]
	v_mad_i64_i32 v[48:49], s[44:45], v48, s61, v[50:51]
	v_lshl_add_u64 v[48:49], v[142:143], 2, v[48:49]
	v_pk_mul_f32 v[46:47], v[46:47], v[64:65] op_sel_hi:[1,0]
	v_pk_mul_f32 v[44:45], v[44:45], v[64:65] op_sel_hi:[1,0]
	v_pk_mul_f32 v[42:43], v[42:43], v[64:65] op_sel_hi:[1,0]
	s_nop 1
	v_pk_mul_f32 v[40:41], v[40:41], v[64:65] op_sel_hi:[1,0]
	v_pk_mul_f32 v[38:39], v[38:39], v[64:65] op_sel_hi:[1,0]
	v_lshl_add_u64 v[48:49], v[48:49], 0, v[244:245]
	s_nop 1
	v_permlane32_swap_b32_e32 v44, v40
	v_permlane32_swap_b32_e32 v45, v41
	v_permlane32_swap_b32_e32 v46, v42
	v_permlane32_swap_b32_e32 v47, v43
	global_store_dwordx4 v[48:49], v[44:47], off sc1
	global_store_dwordx4 v[48:49], v[40:43], off offset:64 sc1
	s_nop 1
	v_lshl_add_u64 v[40:41], v[48:49], 0, s[20:21]
	v_pk_mul_f32 v[36:37], v[36:37], v[64:65] op_sel_hi:[1,0]
	v_pk_mul_f32 v[32:33], v[32:33], v[64:65] op_sel_hi:[1,0]
	s_nop 1
	v_pk_mul_f32 v[34:35], v[34:35], v[64:65] op_sel_hi:[1,0]
	s_nop 0
	s_nop 1
	v_permlane32_swap_b32_e32 v36, v32
	v_permlane32_swap_b32_e32 v37, v33
	v_permlane32_swap_b32_e32 v38, v34
	v_permlane32_swap_b32_e32 v39, v35
	global_store_dwordx4 v[40:41], v[36:39], off sc1
	global_store_dwordx4 v[40:41], v[32:35], off offset:64 sc1
	s_nop 1
	v_add_u32_e32 v33, 0xa0, v164
	v_lshl_add_u32 v136, v33, 5, v149
	v_cmp_lt_i32_e32 vcc, 1, v136
	v_mov_b32_e32 v32, 0
	v_mov_b32_e32 v34, 0
	s_and_saveexec_b64 s[44:45], vcc
	s_cbranch_execz .LBB0_683
	v_lshl_add_u64 v[34:35], v[136:137], 2, s[10:11]
	v_mov_b32_e32 v34, v254
	v_fmamk_f32 v34, v34, 0x3a800000, v163
	v_mul_f32_e32 v35, 0x4b800000, v34
	v_cmp_gt_f32_e32 vcc, s60, v34
	s_nop 1
	v_cndmask_b32_e32 v34, v34, v35, vcc
	v_rsq_f32_e32 v34, v34
	s_nop 0
	v_mul_f32_e32 v35, 0x45800000, v34
	v_cndmask_b32_e32 v34, v34, v35, vcc
.LBB0_683:
	s_or_b64 exec, exec, s[44:45]
	v_mov_b64_e32 v[36:37], s[12:13]
	v_mad_i64_i32 v[36:37], s[44:45], v33, s61, v[36:37]
	v_lshl_add_u64 v[36:37], v[142:143], 2, v[36:37]
	v_pk_mul_f32 v[30:31], v[30:31], v[34:35] op_sel_hi:[1,0]
	v_pk_mul_f32 v[28:29], v[28:29], v[34:35] op_sel_hi:[1,0]
	v_pk_mul_f32 v[26:27], v[26:27], v[34:35] op_sel_hi:[1,0]
	s_nop 1
	v_pk_mul_f32 v[24:25], v[24:25], v[34:35] op_sel_hi:[1,0]
	v_pk_mul_f32 v[22:23], v[22:23], v[34:35] op_sel_hi:[1,0]
	v_lshl_add_u64 v[36:37], v[36:37], 0, v[244:245]
	s_nop 1
	v_permlane32_swap_b32_e32 v28, v24
	v_permlane32_swap_b32_e32 v29, v25
	v_permlane32_swap_b32_e32 v30, v26
	v_permlane32_swap_b32_e32 v31, v27
	global_store_dwordx4 v[36:37], v[28:31], off sc1
	global_store_dwordx4 v[36:37], v[24:27], off offset:64 sc1
	s_nop 1
	v_lshl_add_u64 v[24:25], v[36:37], 0, s[20:21]
	v_pk_mul_f32 v[20:21], v[20:21], v[34:35] op_sel_hi:[1,0]
	v_pk_mul_f32 v[16:17], v[16:17], v[34:35] op_sel_hi:[1,0]
	s_nop 1
	v_pk_mul_f32 v[18:19], v[18:19], v[34:35] op_sel_hi:[1,0]
	s_nop 0
	s_nop 1
	v_permlane32_swap_b32_e32 v20, v16
	v_permlane32_swap_b32_e32 v21, v17
	v_permlane32_swap_b32_e32 v22, v18
	v_permlane32_swap_b32_e32 v23, v19
	global_store_dwordx4 v[24:25], v[20:23], off sc1
	global_store_dwordx4 v[24:25], v[16:19], off offset:64 sc1
	s_nop 1
	v_add_u32_e32 v16, 0xb0, v164
	v_lshl_add_u32 v136, v16, 5, v149
	v_cmp_lt_i32_e32 vcc, 1, v136
	s_and_saveexec_b64 s[44:45], vcc
	s_cbranch_execz .LBB0_685
	v_lshl_add_u64 v[18:19], v[136:137], 2, s[10:11]
	v_mov_b32_e32 v17, v255
	v_fmamk_f32 v17, v17, 0x3a800000, v163
	v_mul_f32_e32 v18, 0x4b800000, v17
	v_cmp_gt_f32_e32 vcc, s60, v17
	s_nop 1
	v_cndmask_b32_e32 v17, v17, v18, vcc
	v_rsq_f32_e32 v17, v17
	s_nop 0
	v_mul_f32_e32 v18, 0x45800000, v17
	v_cndmask_b32_e32 v32, v17, v18, vcc
.LBB0_685:
	s_or_b64 exec, exec, s[44:45]
	v_mov_b64_e32 v[18:19], s[12:13]
	v_mad_i64_i32 v[16:17], s[44:45], v16, s61, v[18:19]
	v_lshl_add_u64 v[16:17], v[142:143], 2, v[16:17]
	v_pk_mul_f32 v[14:15], v[14:15], v[32:33] op_sel_hi:[1,0]
	v_pk_mul_f32 v[12:13], v[12:13], v[32:33] op_sel_hi:[1,0]
	v_pk_mul_f32 v[10:11], v[10:11], v[32:33] op_sel_hi:[1,0]
	s_nop 1
	v_pk_mul_f32 v[8:9], v[8:9], v[32:33] op_sel_hi:[1,0]
	v_pk_mul_f32 v[6:7], v[6:7], v[32:33] op_sel_hi:[1,0]
	v_lshl_add_u64 v[16:17], v[16:17], 0, v[244:245]
	s_nop 1
	v_permlane32_swap_b32_e32 v12, v8
	v_permlane32_swap_b32_e32 v13, v9
	v_permlane32_swap_b32_e32 v14, v10
	v_permlane32_swap_b32_e32 v15, v11
	global_store_dwordx4 v[16:17], v[12:15], off sc1
	global_store_dwordx4 v[16:17], v[8:11], off offset:64 sc1
	s_nop 1
	v_lshl_add_u64 v[8:9], v[16:17], 0, s[20:21]
	v_pk_mul_f32 v[4:5], v[4:5], v[32:33] op_sel_hi:[1,0]
	v_pk_mul_f32 v[2:3], v[2:3], v[32:33] op_sel_hi:[1,0]
	s_nop 1
	v_pk_mul_f32 v[0:1], v[0:1], v[32:33] op_sel_hi:[1,0]
	s_nop 0
	s_nop 1
	v_permlane32_swap_b32_e32 v4, v0
	v_permlane32_swap_b32_e32 v5, v1
	v_permlane32_swap_b32_e32 v6, v2
	v_permlane32_swap_b32_e32 v7, v3
	global_store_dwordx4 v[8:9], v[4:7], off sc1
	global_store_dwordx4 v[8:9], v[0:3], off offset:64 sc1
	s_nop 1
	s_waitcnt vmcnt(0)
	s_barrier
	s_and_saveexec_b64 s[44:45], s[90:91]
	s_cbranch_execz .LBB0_688
	s_mov_b64 s[46:47], exec
	v_mbcnt_lo_u32_b32 v0, s46, 0
	v_mbcnt_hi_u32_b32 v0, s47, v0
	v_cmp_eq_u32_e32 vcc, 0, v0
	s_and_b64 s[48:49], exec, vcc
	s_mov_b64 exec, s[48:49]
	s_cbranch_execz .LBB0_688
	s_bcnt1_i32_b64 s23, s[46:47]
	v_mov_b32_e32 v0, s23
	global_atomic_add v137, v0, s[14:15]
